# mqk (LDS weights) preceded by a bulk pull of the tile's 256 KiB of XM rows into cache (all loads in flight)
# speedup vs baseline: 1.0090x; 1.0090x over previous
; #define MQ_LOAD(dst, mm) do { const int tk_ = row0 + 16 * (mm) + (lane & 15), s_ = tk_ & (SEQL - 1); \
;                 _Pragma("unroll") for (int j = 0; j < 4; ++j) dst[j] = (s_ - 3 + j >= 0) ? *(const u32x4*)(XM + (size_t)(tk_ - 3 + j) * 2048 + c0) : (u32x4){0u, 0u, 0u, 0u}; } while (0)
; __device__ void mqk_phase(const Params& p, unsigned char* smem) {
;     ...
;     for (int tile = blockIdx.x; tile < 256; tile += gridDim.x) {
;         const int row0 = tile * 64;
;         f32x4 acc[4];
; #pragma unroll
;         for (int m = 0; m < 4; ++m) acc[m] = (f32x4){0.f, 0.f, 0.f, 0.f};
;         for (int ks = 0; ks < 8; ++ks) {
;             const int c0 = 256 * wave + 32 * ks + 8 * (lane >> 4);
;             float cw[4][8], cbv[8];
; #pragma unroll
;             for (int j = 0; j < 4; ++j) { const f32x4 a = *(const f32x4*)(p.in[10] + j * 2048 + c0), b = *(const f32x4*)(p.in[10] + j * 2048 + c0 + 4);
; #pragma unroll
;                 for (int i = 0; i < 4; ++i) { cw[j][i] = a[i]; cw[j][4 + i] = b[i]; } }
;             { const f32x4 a = *(const f32x4*)(p.in[11] + c0), b = *(const f32x4*)(p.in[11] + c0 + 4);
; #pragma unroll
;               for (int i = 0; i < 4; ++i) { cbv[i] = a[i]; cbv[4 + i] = b[i]; } }
;             const bf16x8 bq = *(const bf16x8*)(WG + (size_t)(lane & 15) * 6144 + c0), bk = *(const bf16x8*)(WG + (size_t)(lane & 15) * 6144 + 2048 + c0), bv = *(const bf16x8*)(WG + (size_t)(lane & 15) * 6144 + 4096 + c0);
;             const float* wqp = p.in[12] + (size_t)(c0 >> 2) * 16; const float* wkp = p.in[13] + (size_t)(c0 >> 2) * 16; const float* wvp = p.in[14] + (size_t)(c0 >> 2) * 16;
;             u32x4 xraw[4];
;     ...
;             MQ_LOAD(xraw, 0);
; #pragma unroll
;             for (int m = 0; m < 4; ++m) {
;                 const int tk = row0 + 16 * m + (lane & 15);
.LBB0_299:
	s_lshl_b32 s2, s50, 18
	v_and_b32_e32 v130, 0x3ff, v0
	v_lshlrev_b32_e32 v130, 4, v130
	v_add_u32_e32 v130, s2, v130
	global_load_dwordx4 v[2:5], v130, s[0:1]
	v_add_u32_e32 v130, 0x2000, v130
	global_load_dwordx4 v[2:5], v130, s[0:1]
	v_add_u32_e32 v130, 0x2000, v130
	global_load_dwordx4 v[2:5], v130, s[0:1]
	v_add_u32_e32 v130, 0x2000, v130
	global_load_dwordx4 v[2:5], v130, s[0:1]
	v_add_u32_e32 v130, 0x2000, v130
	global_load_dwordx4 v[2:5], v130, s[0:1]
	v_add_u32_e32 v130, 0x2000, v130
	global_load_dwordx4 v[2:5], v130, s[0:1]
	v_add_u32_e32 v130, 0x2000, v130
	global_load_dwordx4 v[2:5], v130, s[0:1]
	v_add_u32_e32 v130, 0x2000, v130
	global_load_dwordx4 v[2:5], v130, s[0:1]
	v_add_u32_e32 v130, 0x2000, v130
	global_load_dwordx4 v[2:5], v130, s[0:1]
	v_add_u32_e32 v130, 0x2000, v130
	global_load_dwordx4 v[2:5], v130, s[0:1]
	v_add_u32_e32 v130, 0x2000, v130
	global_load_dwordx4 v[2:5], v130, s[0:1]
	v_add_u32_e32 v130, 0x2000, v130
	global_load_dwordx4 v[2:5], v130, s[0:1]
	v_add_u32_e32 v130, 0x2000, v130
	global_load_dwordx4 v[2:5], v130, s[0:1]
	v_add_u32_e32 v130, 0x2000, v130
	global_load_dwordx4 v[2:5], v130, s[0:1]
	v_add_u32_e32 v130, 0x2000, v130
	global_load_dwordx4 v[2:5], v130, s[0:1]
	v_add_u32_e32 v130, 0x2000, v130
	global_load_dwordx4 v[2:5], v130, s[0:1]
	v_add_u32_e32 v130, 0x2000, v130
	global_load_dwordx4 v[2:5], v130, s[0:1]
	v_add_u32_e32 v130, 0x2000, v130
	global_load_dwordx4 v[2:5], v130, s[0:1]
	v_add_u32_e32 v130, 0x2000, v130
	global_load_dwordx4 v[2:5], v130, s[0:1]
	v_add_u32_e32 v130, 0x2000, v130
	global_load_dwordx4 v[2:5], v130, s[0:1]
	v_add_u32_e32 v130, 0x2000, v130
	global_load_dwordx4 v[2:5], v130, s[0:1]
	v_add_u32_e32 v130, 0x2000, v130
	global_load_dwordx4 v[2:5], v130, s[0:1]
	v_add_u32_e32 v130, 0x2000, v130
	global_load_dwordx4 v[2:5], v130, s[0:1]
	v_add_u32_e32 v130, 0x2000, v130
	global_load_dwordx4 v[2:5], v130, s[0:1]
	v_add_u32_e32 v130, 0x2000, v130
	global_load_dwordx4 v[2:5], v130, s[0:1]
	v_add_u32_e32 v130, 0x2000, v130
	global_load_dwordx4 v[2:5], v130, s[0:1]
	v_add_u32_e32 v130, 0x2000, v130
	global_load_dwordx4 v[2:5], v130, s[0:1]
	v_add_u32_e32 v130, 0x2000, v130
	global_load_dwordx4 v[2:5], v130, s[0:1]
	v_add_u32_e32 v130, 0x2000, v130
	global_load_dwordx4 v[2:5], v130, s[0:1]
	v_add_u32_e32 v130, 0x2000, v130
	global_load_dwordx4 v[2:5], v130, s[0:1]
	v_add_u32_e32 v130, 0x2000, v130
	global_load_dwordx4 v[2:5], v130, s[0:1]
	v_add_u32_e32 v130, 0x2000, v130
	global_load_dwordx4 v[2:5], v130, s[0:1]
	v_add_u32_e32 v130, 0x2000, v130
	v_and_b32_e32 v118, 0x3ff, v0
	v_lshlrev_b32_e32 v118, 4, v118
	v_add_u32_e32 v119, 0x2000, v118
	v_add_u32_e32 v120, 0x4000, v118
	v_add_u32_e32 v121, 0x6000, v118
	global_load_dwordx4 v[70:73], v118, s[80:81]
	global_load_dwordx4 v[74:77], v119, s[80:81]
	global_load_dwordx4 v[78:81], v120, s[80:81]
	global_load_dwordx4 v[82:85], v121, s[80:81]
	global_load_dwordx4 v[86:89], v118, s[76:77]
	global_load_dwordx4 v[90:93], v119, s[76:77]
	global_load_dwordx4 v[94:97], v120, s[76:77]
	global_load_dwordx4 v[98:101], v121, s[76:77]
	global_load_dwordx4 v[102:105], v118, s[78:79]
	global_load_dwordx4 v[106:109], v119, s[78:79]
	global_load_dwordx4 v[110:113], v120, s[78:79]
	global_load_dwordx4 v[114:117], v121, s[78:79]
	s_waitcnt vmcnt(0)
	ds_write_b128 v118, v[70:73] offset:32768
	ds_write_b128 v119, v[74:77] offset:32768
	ds_write_b128 v120, v[78:81] offset:32768
	ds_write_b128 v121, v[82:85] offset:32768
	v_add_u32_e32 v118, 0x10000, v118
	v_add_u32_e32 v119, 0x10000, v119
	v_add_u32_e32 v120, 0x10000, v120
	v_add_u32_e32 v121, 0x10000, v121
	ds_write_b128 v118, v[86:89]
	ds_write_b128 v119, v[90:93]
	ds_write_b128 v120, v[94:97]
	ds_write_b128 v121, v[98:101]
	ds_write_b128 v118, v[102:105] offset:32768
	ds_write_b128 v119, v[106:109] offset:32768
	ds_write_b128 v120, v[110:113] offset:32768
	ds_write_b128 v121, v[114:117] offset:32768
	s_waitcnt lgkmcnt(0)
	s_barrier
	s_lshl_b32 s2, s50, 6
	v_or_b32_e32 v2, s2, v229
	v_ashrrev_i32_e32 v3, 31, v2
	v_bitop3_b32 v5, s2, v232, v229 bitop3:0xc8
	v_or_b32_e32 v4, 16, v2
	v_lshlrev_b64 v[174:175], 12, v[2:3]
	v_lshlrev_b64 v[6:7], 11, v[2:3]
	v_or_b32_e32 v8, 32, v2
	v_or_b32_e32 v2, 48, v2
	v_cmp_lt_u32_e32 vcc, 2, v5
	v_cmp_lt_u32_e64 s[2:3], 1, v5
	v_cmp_ne_u32_e64 s[4:5], 0, v5
	v_ashrrev_i32_e32 v5, 31, v4
	v_ashrrev_i32_e32 v9, 31, v8
	v_ashrrev_i32_e32 v3, 31, v2
	v_lshlrev_b64 v[188:189], 12, v[4:5]
	v_lshlrev_b64 v[196:197], 12, v[8:9]
	v_lshlrev_b64 v[4:5], 11, v[4:5]
	v_lshlrev_b64 v[204:205], 12, v[2:3]
	v_lshlrev_b64 v[8:9], 11, v[8:9]
	v_lshlrev_b64 v[2:3], 11, v[2:3]
	v_lshl_add_u64 v[176:177], v[174:175], 0, s[14:15]
	v_lshl_add_u64 v[178:179], v[174:175], 0, s[16:17]
	v_lshl_add_u64 v[180:181], v[174:175], 0, s[18:19]
	v_lshl_add_u64 v[182:183], v[174:175], 0, s[20:21]
	v_lshl_add_u64 v[184:185], v[174:175], 0, s[22:23]
	v_lshl_add_u64 v[186:187], v[174:175], 0, s[24:25]
	v_lshl_add_u64 v[190:191], v[174:175], 0, s[26:27]
	v_lshl_add_u64 v[192:193], v[174:175], 0, s[28:29]
	v_lshl_add_u64 v[194:195], v[174:175], 0, s[30:31]
	v_lshl_add_u64 v[198:199], v[174:175], 0, s[34:35]
	v_lshl_add_u64 v[200:201], v[174:175], 0, s[36:37]
	v_lshl_add_u64 v[202:203], v[174:175], 0, s[38:39]
	v_lshlrev_b64 v[206:207], 1, v[6:7]
	v_lshlrev_b64 v[208:209], 1, v[4:5]
	v_lshlrev_b64 v[210:211], 1, v[8:9]
	v_lshlrev_b64 v[212:213], 1, v[2:3]
	s_mov_b32 s51, 0
	v_mov_b32_e32 v66, v163
	v_mov_b32_e32 v67, v163
	v_mov_b32_e32 v68, v163
	v_mov_b32_e32 v69, v163
	v_mov_b32_e32 v62, v163
	v_mov_b32_e32 v63, v163
	v_mov_b32_e32 v64, v163
	v_mov_b32_e32 v65, v163
	v_mov_b32_e32 v2, v163
	v_mov_b32_e32 v3, v163
	v_mov_b32_e32 v4, v163
	v_mov_b32_e32 v5, v163
	v_mov_b32_e32 v6, v163
	v_mov_b32_e32 v7, v163
	v_mov_b32_e32 v8, v163
	v_mov_b32_e32 v9, v163
	s_branch .LBB0_301
